# attention softmax segment: straight-line common path (mask/rescale blocks out of line), inactive flag via s_not
# speedup vs baseline: 1.0466x; 1.0067x over previous
.LBB0_1037:
	s_add_i32 s1, s59, 3
	s_cmp_lt_u32 s1, s49
	s_cselect_b32 s1, s1, s50
	s_lshl_b32 s8, s1, 6
	v_add_u32_e32 v0, s8, v150
	v_mad_i64_i32 v[94:95], s[4:5], v0, s3, v[144:145]
	v_add_u32_e32 v0, s8, v151
	v_mad_i64_i32 v[96:97], s[4:5], v0, s3, v[146:147]
	v_lshl_add_u64 v[102:103], s[8:9], 1, v[142:143]
	global_load_dwordx4 v[98:101], v[94:95], off
	s_nop 0
	global_load_dwordx4 v[94:97], v[96:97], off
	s_add_i32 s62, s55, s59
	global_load_dwordx4 v[102:105], v[102:103], off
	s_cmp_lt_i32 s62, 0
	s_cselect_b64 s[18:19], -1, 0
	s_add_i32 s61, s56, s54
	s_cmp_le_i32 s61, s51
	s_cselect_b64 s[4:5], -1, 0
	s_or_b64 s[20:21], s[18:19], s[4:5]
	s_mov_b32 s60, s58
	s_not_b64 s[4:5], s[20:21]
	s_andn2_b64 vcc, exec, s[20:21]
	s_mov_b32 s58, s0
	v_add_u32_e32 v248, s58, v160
	ds_read_b128 v[164:167], v248 offset:13312
	ds_read_b128 v[168:171], v248 offset:17920
	ds_read_b128 v[172:175], v248 offset:13344
	ds_read_b128 v[176:179], v248 offset:17952
	ds_read_b128 v[180:183], v248 offset:13376
	ds_read_b128 v[220:223], v248 offset:17984
	ds_read_b128 v[224:227], v248 offset:13408
	ds_read_b128 v[232:235], v248 offset:18016
	s_cbranch_vccnz .LBB0_1049
	s_cmp_lt_i32 s62, 0
	s_cbranch_scc0 .Lmla_a_mask
.LBB0_1040:
	v_max3_f32 v0, v34, v35, v36
	v_max3_f32 v122, v50, v51, v52
	v_max3_f32 v0, v0, v37, v38
	v_max3_f32 v122, v122, v53, v54
	v_max3_f32 v0, v0, v39, v40
	v_max3_f32 v122, v122, v55, v56
	v_max3_f32 v0, v0, v41, v42
	v_max3_f32 v122, v122, v57, v58
	v_max3_f32 v0, v0, v43, v44
	v_max3_f32 v122, v122, v59, v60
	v_max3_f32 v0, v0, v45, v46
	v_max3_f32 v122, v122, v61, v62
	v_max_f32_e32 v123, v65, v65
	v_max_f32_e32 v124, v49, v49
	v_max3_f32 v0, v0, v47, v48
	v_max3_f32 v122, v122, v63, v64
	v_max_f32_e32 v123, v124, v123
	v_max3_f32 v0, v0, v122, v123
	s_cmp_lg_u32 s54, 0
	s_cselect_b64 s[20:21], -1, 0
	s_cmp_eq_u32 s54, 0
	s_cbranch_scc1 .Lmla_a_xchg
	v_cmp_lt_f32_e32 vcc, s35, v0
	s_cbranch_vccnz .Lmla_a_xchg

.LBB0_1053:
	s_setprio 0
	s_add_i32 s0, s59, 4
	s_cmp_lt_u32 s59, s48
	s_cselect_b32 s0, s0, s50
	s_lshl_b32 s8, s0, 6
	v_add_u32_e32 v0, s8, v150
	s_waitcnt lgkmcnt(0)
	s_barrier
	v_mad_i64_i32 v[82:83], s[0:1], v0, s3, v[144:145]
	v_add_u32_e32 v0, s8, v151
	v_mad_i64_i32 v[84:85], s[0:1], v0, s3, v[146:147]
	global_load_dwordx4 v[86:89], v[82:83], off
	global_load_dwordx4 v[90:93], v[84:85], off
	v_lshl_add_u64 v[82:83], s[8:9], 1, v[142:143]
	global_load_dwordx4 v[82:85], v[82:83], off
	v_add_u32_e32 v248, s60, v160
	ds_read_b128 v[164:167], v248 offset:13312
	ds_read_b128 v[168:171], v248 offset:17920
	ds_read_b128 v[172:175], v248 offset:13344
	ds_read_b128 v[176:179], v248 offset:17952
	ds_read_b128 v[180:183], v248 offset:13376
	ds_read_b128 v[220:223], v248 offset:17984
	ds_read_b128 v[224:227], v248 offset:13408
	ds_read_b128 v[232:235], v248 offset:18016
	s_add_i32 s62, s62, 1
	s_cmp_lt_i32 s62, 0
	s_cselect_b64 s[0:1], -1, 0
	s_add_i32 s4, s61, 64
	s_cmp_le_i32 s4, s51
	s_cselect_b64 s[4:5], -1, 0
	s_or_b64 s[0:1], s[0:1], s[4:5]
	s_not_b64 s[4:5], s[0:1]
	s_andn2_b64 vcc, exec, s[0:1]
	s_cbranch_vccnz .LBB0_1059
	s_cmp_lt_i32 s62, 0
	s_cbranch_scc0 .Lmla_b_mask
.LBB0_1056:
	v_max3_f32 v0, v34, v35, v36
	v_max3_f32 v106, v50, v51, v52
	v_max3_f32 v0, v0, v37, v38
	v_max3_f32 v106, v106, v53, v54
	v_max3_f32 v0, v0, v39, v40
	v_max3_f32 v106, v106, v55, v56
	v_max3_f32 v0, v0, v41, v42
	v_max3_f32 v106, v106, v57, v58
	v_max3_f32 v0, v0, v43, v44
	v_max3_f32 v106, v106, v59, v60
	v_max3_f32 v0, v0, v45, v46
	v_max3_f32 v106, v106, v61, v62
	v_max_f32_e32 v107, v65, v65
	v_max_f32_e32 v108, v49, v49
	v_max3_f32 v0, v0, v47, v48
	v_max3_f32 v106, v106, v63, v64
	v_max_f32_e32 v107, v108, v107
	v_max3_f32 v0, v0, v106, v107
	v_cmp_lt_f32_e32 vcc, s35, v0
	s_cbranch_vccnz .Lmla_b_resc

.Lmla_a_mask:
	v_add_u32_e32 v0, s54, v161
	v_add_u32_e32 v122, 32, v0
	v_cmp_le_i32_e32 vcc, v122, v159
	v_add_u32_e32 v122, 33, v0
	s_nop 0
	v_cndmask_b32_e32 v50, v149, v50, vcc
	v_cmp_lt_i32_e32 vcc, v0, v159
	s_nop 1
	v_cndmask_b32_e32 v35, v149, v35, vcc
	v_cmp_le_i32_e32 vcc, v0, v159
	s_nop 1
	v_cndmask_b32_e32 v34, v149, v34, vcc
	v_cmp_le_i32_e32 vcc, v122, v159
	v_add_u32_e32 v122, 2, v0
	s_nop 0
	v_cndmask_b32_e32 v51, v149, v51, vcc
	v_cmp_le_i32_e32 vcc, v122, v159
	v_add_u32_e32 v122, 34, v0
	s_nop 0
	v_cndmask_b32_e32 v36, v149, v36, vcc
	v_cmp_le_i32_e32 vcc, v122, v159
	v_add_u32_e32 v122, 3, v0
	s_nop 0
	v_cndmask_b32_e32 v52, v149, v52, vcc
	v_cmp_le_i32_e32 vcc, v122, v159
	v_add_u32_e32 v122, 35, v0
	s_nop 0
	v_cndmask_b32_e32 v37, v149, v37, vcc
	v_cmp_le_i32_e32 vcc, v122, v159
	v_add_u32_e32 v122, 8, v0
	s_nop 0
	v_cndmask_b32_e32 v53, v149, v53, vcc
	v_cmp_le_i32_e32 vcc, v122, v159
	v_add_u32_e32 v122, 40, v0
	s_nop 0
	v_cndmask_b32_e32 v38, v149, v38, vcc
	v_cmp_le_i32_e32 vcc, v122, v159
	v_add_u32_e32 v122, 9, v0
	s_nop 0
	v_cndmask_b32_e32 v54, v149, v54, vcc
	v_cmp_le_i32_e32 vcc, v122, v159
	v_add_u32_e32 v122, 41, v0
	s_nop 0
	v_cndmask_b32_e32 v39, v149, v39, vcc
	v_cmp_le_i32_e32 vcc, v122, v159
	v_add_u32_e32 v122, 10, v0
	s_nop 0
	v_cndmask_b32_e32 v55, v149, v55, vcc
	v_cmp_le_i32_e32 vcc, v122, v159
	v_add_u32_e32 v122, 42, v0
	s_nop 0
	v_cndmask_b32_e32 v40, v149, v40, vcc
	v_cmp_le_i32_e32 vcc, v122, v159
	v_add_u32_e32 v122, 11, v0
	s_nop 0
	v_cndmask_b32_e32 v56, v149, v56, vcc
	v_cmp_le_i32_e32 vcc, v122, v159
	v_add_u32_e32 v122, 43, v0
	s_nop 0
	v_cndmask_b32_e32 v41, v149, v41, vcc
	v_cmp_le_i32_e32 vcc, v122, v159
	v_add_u32_e32 v122, 16, v0
	s_nop 0
	v_cndmask_b32_e32 v57, v149, v57, vcc
	v_cmp_le_i32_e32 vcc, v122, v159
	v_add_u32_e32 v122, 48, v0
	s_nop 0
	v_cndmask_b32_e32 v42, v149, v42, vcc
	v_cmp_le_i32_e32 vcc, v122, v159
	v_add_u32_e32 v122, 17, v0
	s_nop 0
	v_cndmask_b32_e32 v58, v149, v58, vcc
	v_cmp_le_i32_e32 vcc, v122, v159
	v_add_u32_e32 v122, 49, v0
	s_nop 0
	v_cndmask_b32_e32 v43, v149, v43, vcc
	v_cmp_le_i32_e32 vcc, v122, v159
	v_add_u32_e32 v122, 18, v0
	s_nop 0
	v_cndmask_b32_e32 v59, v149, v59, vcc
	v_cmp_le_i32_e32 vcc, v122, v159
	v_add_u32_e32 v122, 50, v0
	s_nop 0
	v_cndmask_b32_e32 v44, v149, v44, vcc
	v_cmp_le_i32_e32 vcc, v122, v159
	v_add_u32_e32 v122, 19, v0
	s_nop 0
	v_cndmask_b32_e32 v60, v149, v60, vcc
	v_cmp_le_i32_e32 vcc, v122, v159
	v_add_u32_e32 v122, 51, v0
	s_nop 0
	v_cndmask_b32_e32 v45, v149, v45, vcc
	v_cmp_le_i32_e32 vcc, v122, v159
	v_add_u32_e32 v122, 24, v0
	s_nop 0
	v_cndmask_b32_e32 v61, v149, v61, vcc
	v_cmp_le_i32_e32 vcc, v122, v159
	v_add_u32_e32 v122, 56, v0
	s_nop 0
	v_cndmask_b32_e32 v46, v149, v46, vcc
	v_cmp_le_i32_e32 vcc, v122, v159
	v_add_u32_e32 v122, 25, v0
	s_nop 0
	v_cndmask_b32_e32 v62, v149, v62, vcc
	v_cmp_le_i32_e32 vcc, v122, v159
	v_add_u32_e32 v122, 57, v0
	s_nop 0
	v_cndmask_b32_e32 v47, v149, v47, vcc
	v_cmp_le_i32_e32 vcc, v122, v159
	v_add_u32_e32 v122, 26, v0
	s_nop 0
	v_cndmask_b32_e32 v63, v149, v63, vcc
	v_cmp_le_i32_e32 vcc, v122, v159
	v_add_u32_e32 v122, 58, v0
	s_nop 0
	v_cndmask_b32_e32 v48, v149, v48, vcc
	v_cmp_le_i32_e32 vcc, v122, v159
	v_add_u32_e32 v122, 27, v0
	v_add_u32_e32 v0, 59, v0
	v_cndmask_b32_e32 v64, v149, v64, vcc
	v_cmp_le_i32_e32 vcc, v122, v159
	s_nop 1
	v_cndmask_b32_e32 v49, v149, v49, vcc
	v_cmp_le_i32_e32 vcc, v0, v159
	s_nop 1
	v_cndmask_b32_e32 v65, v149, v65, vcc
	s_branch .LBB0_1040

.LBB0_1047:
	v_add_f32_e32 v163, v163, v0
	v_xor_b32_e32 v66, 0x80000000, v163
	v_sub_f32_e32 v49, v49, v0
	v_sub_f32_e32 v48, v48, v0
	v_sub_f32_e32 v47, v47, v0
	v_sub_f32_e32 v46, v46, v0
	v_sub_f32_e32 v45, v45, v0
	v_sub_f32_e32 v44, v44, v0
	v_sub_f32_e32 v43, v43, v0
	v_sub_f32_e32 v42, v42, v0
	v_sub_f32_e32 v41, v41, v0
	v_sub_f32_e32 v40, v40, v0
	v_sub_f32_e32 v39, v39, v0
	v_sub_f32_e32 v38, v38, v0
	v_sub_f32_e32 v37, v37, v0
	v_sub_f32_e32 v36, v36, v0
	v_sub_f32_e32 v35, v35, v0
	v_sub_f32_e32 v34, v34, v0
	v_sub_f32_e32 v65, v65, v0
	v_sub_f32_e32 v64, v64, v0
	v_sub_f32_e32 v63, v63, v0
	v_sub_f32_e32 v62, v62, v0
	v_sub_f32_e32 v61, v61, v0
	v_sub_f32_e32 v60, v60, v0
	v_sub_f32_e32 v59, v59, v0
	v_sub_f32_e32 v58, v58, v0
	v_sub_f32_e32 v57, v57, v0
	v_sub_f32_e32 v56, v56, v0
	v_sub_f32_e32 v55, v55, v0
	v_sub_f32_e32 v54, v54, v0
	v_sub_f32_e32 v53, v53, v0
	v_sub_f32_e32 v52, v52, v0
	v_sub_f32_e32 v51, v51, v0
	v_sub_f32_e32 v50, v50, v0
	v_mov_b32_e32 v67, v66
	v_mov_b32_e32 v68, v66
	v_mov_b32_e32 v69, v66
	v_mov_b32_e32 v70, v66
	v_mov_b32_e32 v71, v66
	v_mov_b32_e32 v72, v66
	v_mov_b32_e32 v73, v66
	v_mov_b32_e32 v74, v66
	v_mov_b32_e32 v75, v66
	v_mov_b32_e32 v76, v66
	v_mov_b32_e32 v77, v66
	v_mov_b32_e32 v78, v66
	v_mov_b32_e32 v79, v66
	v_mov_b32_e32 v80, v66
	v_mov_b32_e32 v81, v66
	s_branch .LBB0_1048
.Lmla_b_mask:
	v_add_u32_e32 v0, s54, v161
	v_add_u32_e32 v107, 0x60, v0
	v_add_u32_e32 v106, 64, v0
	v_cmp_le_i32_e32 vcc, v107, v159
	s_nop 1
	v_cndmask_b32_e32 v50, v149, v50, vcc
	v_cmp_lt_i32_e32 vcc, v106, v159
	s_nop 1
	v_cndmask_b32_e32 v35, v149, v35, vcc
	v_cmp_le_i32_e32 vcc, v106, v159
	v_add_u32_e32 v106, 0x61, v0
	s_nop 0
	v_cndmask_b32_e32 v34, v149, v34, vcc
	v_cmp_le_i32_e32 vcc, v106, v159
	v_add_u32_e32 v106, 0x42, v0
	s_nop 0
	v_cndmask_b32_e32 v51, v149, v51, vcc
	v_cmp_le_i32_e32 vcc, v106, v159
	v_add_u32_e32 v106, 0x62, v0
	s_nop 0
	v_cndmask_b32_e32 v36, v149, v36, vcc
	v_cmp_le_i32_e32 vcc, v106, v159
	v_add_u32_e32 v106, 0x43, v0
	s_nop 0
	v_cndmask_b32_e32 v52, v149, v52, vcc
	v_cmp_le_i32_e32 vcc, v106, v159
	v_add_u32_e32 v106, 0x63, v0
	s_nop 0
	v_cndmask_b32_e32 v37, v149, v37, vcc
	v_cmp_le_i32_e32 vcc, v106, v159
	v_add_u32_e32 v106, 0x48, v0
	s_nop 0
	v_cndmask_b32_e32 v53, v149, v53, vcc
	v_cmp_le_i32_e32 vcc, v106, v159
	v_add_u32_e32 v106, 0x68, v0
	s_nop 0
	v_cndmask_b32_e32 v38, v149, v38, vcc
	v_cmp_le_i32_e32 vcc, v106, v159
	v_add_u32_e32 v106, 0x49, v0
	s_nop 0
	v_cndmask_b32_e32 v54, v149, v54, vcc
	v_cmp_le_i32_e32 vcc, v106, v159
	v_add_u32_e32 v106, 0x69, v0
	s_nop 0
	v_cndmask_b32_e32 v39, v149, v39, vcc
	v_cmp_le_i32_e32 vcc, v106, v159
	v_add_u32_e32 v106, 0x4a, v0
	s_nop 0
	v_cndmask_b32_e32 v55, v149, v55, vcc
	v_cmp_le_i32_e32 vcc, v106, v159
	v_add_u32_e32 v106, 0x6a, v0
	s_nop 0
	v_cndmask_b32_e32 v40, v149, v40, vcc
	v_cmp_le_i32_e32 vcc, v106, v159
	v_add_u32_e32 v106, 0x4b, v0
	s_nop 0
	v_cndmask_b32_e32 v56, v149, v56, vcc
	v_cmp_le_i32_e32 vcc, v106, v159
	v_add_u32_e32 v106, 0x6b, v0
	s_nop 0
	v_cndmask_b32_e32 v41, v149, v41, vcc
	v_cmp_le_i32_e32 vcc, v106, v159
	v_add_u32_e32 v106, 0x50, v0
	s_nop 0
	v_cndmask_b32_e32 v57, v149, v57, vcc
	v_cmp_le_i32_e32 vcc, v106, v159
	v_add_u32_e32 v106, 0x70, v0
	s_nop 0
	v_cndmask_b32_e32 v42, v149, v42, vcc
	v_cmp_le_i32_e32 vcc, v106, v159
	v_add_u32_e32 v106, 0x51, v0
	s_nop 0
	v_cndmask_b32_e32 v58, v149, v58, vcc
	v_cmp_le_i32_e32 vcc, v106, v159
	v_add_u32_e32 v106, 0x71, v0
	s_nop 0
	v_cndmask_b32_e32 v43, v149, v43, vcc
	v_cmp_le_i32_e32 vcc, v106, v159
	v_add_u32_e32 v106, 0x52, v0
	s_nop 0
	v_cndmask_b32_e32 v59, v149, v59, vcc
	v_cmp_le_i32_e32 vcc, v106, v159
	v_add_u32_e32 v106, 0x72, v0
	s_nop 0
	v_cndmask_b32_e32 v44, v149, v44, vcc
	v_cmp_le_i32_e32 vcc, v106, v159
	v_add_u32_e32 v106, 0x53, v0
	s_nop 0
	v_cndmask_b32_e32 v60, v149, v60, vcc
	v_cmp_le_i32_e32 vcc, v106, v159
	v_add_u32_e32 v106, 0x73, v0
	s_nop 0
	v_cndmask_b32_e32 v45, v149, v45, vcc
	v_cmp_le_i32_e32 vcc, v106, v159
	v_add_u32_e32 v106, 0x58, v0
	s_nop 0
	v_cndmask_b32_e32 v61, v149, v61, vcc
	v_cmp_le_i32_e32 vcc, v106, v159
	v_add_u32_e32 v106, 0x78, v0
	s_nop 0
	v_cndmask_b32_e32 v46, v149, v46, vcc
	v_cmp_le_i32_e32 vcc, v106, v159
	v_add_u32_e32 v106, 0x59, v0
	s_nop 0
	v_cndmask_b32_e32 v62, v149, v62, vcc
	v_cmp_le_i32_e32 vcc, v106, v159
	v_add_u32_e32 v106, 0x79, v0
	s_nop 0
	v_cndmask_b32_e32 v47, v149, v47, vcc
	v_cmp_le_i32_e32 vcc, v106, v159
	v_add_u32_e32 v106, 0x5a, v0
	s_nop 0
	v_cndmask_b32_e32 v63, v149, v63, vcc
	v_cmp_le_i32_e32 vcc, v106, v159
	v_add_u32_e32 v106, 0x7a, v0
	s_nop 0
	v_cndmask_b32_e32 v48, v149, v48, vcc
	v_cmp_le_i32_e32 vcc, v106, v159
	v_add_u32_e32 v106, 0x5b, v0
	v_add_u32_e32 v0, 0x7b, v0
	v_cndmask_b32_e32 v64, v149, v64, vcc
	v_cmp_le_i32_e32 vcc, v106, v159
	s_nop 1
	v_cndmask_b32_e32 v49, v149, v49, vcc
	v_cmp_le_i32_e32 vcc, v0, v159
	s_nop 1
	v_cndmask_b32_e32 v65, v149, v65, vcc
	s_branch .LBB0_1056
.Lmla_b_resc:
	v_and_b32_e32 v107, 64, v148
	v_xor_b32_e32 v106, 32, v148
	v_add_u32_e32 v107, 64, v107
	v_cmp_lt_i32_e32 vcc, v106, v107
	s_nop 1
	v_cndmask_b32_e32 v106, v148, v106, vcc
	v_lshlrev_b32_e32 v106, 2, v106
	ds_bpermute_b32 v106, v106, v0
	s_waitcnt lgkmcnt(0)
	v_max_f32_e32 v106, v106, v106
	v_max_f32_e32 v0, v0, v106
	v_max_f32_e32 v0, v0, v0
	v_max_f32_e32 v66, 0, v0
	v_exp_f32_e64 v0, -v66
	v_add_f32_e32 v163, v163, v66
	v_sub_f32_e32 v49, v49, v66
	v_sub_f32_e32 v48, v48, v66
	v_sub_f32_e32 v47, v47, v66
	v_sub_f32_e32 v46, v46, v66
	v_sub_f32_e32 v45, v45, v66
	v_sub_f32_e32 v44, v44, v66
	v_sub_f32_e32 v43, v43, v66
	v_sub_f32_e32 v42, v42, v66
	v_sub_f32_e32 v41, v41, v66
	v_sub_f32_e32 v40, v40, v66
	v_sub_f32_e32 v39, v39, v66
	v_sub_f32_e32 v38, v38, v66
	v_sub_f32_e32 v37, v37, v66
	v_sub_f32_e32 v36, v36, v66
	v_sub_f32_e32 v35, v35, v66
	v_sub_f32_e32 v34, v34, v66
	v_sub_f32_e32 v65, v65, v66
	v_sub_f32_e32 v64, v64, v66
	v_sub_f32_e32 v63, v63, v66
	v_sub_f32_e32 v62, v62, v66
	v_sub_f32_e32 v61, v61, v66
	v_sub_f32_e32 v60, v60, v66
	v_sub_f32_e32 v59, v59, v66
	v_sub_f32_e32 v58, v58, v66
	v_sub_f32_e32 v57, v57, v66
	v_sub_f32_e32 v56, v56, v66
	v_sub_f32_e32 v55, v55, v66
	v_sub_f32_e32 v54, v54, v66
	v_sub_f32_e32 v53, v53, v66
	v_sub_f32_e32 v52, v52, v66
	v_sub_f32_e32 v51, v51, v66
	v_sub_f32_e32 v50, v50, v66
	v_xor_b32_e32 v66, 0x80000000, v163
	v_mov_b32_e32 v67, v66
	v_mov_b32_e32 v68, v66
	v_mov_b32_e32 v69, v66
	v_mov_b32_e32 v70, v66
	v_mov_b32_e32 v71, v66
	v_mov_b32_e32 v72, v66
	v_mov_b32_e32 v73, v66
	v_mov_b32_e32 v74, v66
	v_mov_b32_e32 v75, v66
	v_mov_b32_e32 v76, v66
	v_mov_b32_e32 v77, v66
	v_mov_b32_e32 v78, v66
	v_mov_b32_e32 v79, v66
	v_mov_b32_e32 v80, v66
	v_mov_b32_e32 v81, v66
	v_pk_mul_f32 v[32:33], v[32:33], v[0:1] op_sel_hi:[1,0]
	v_pk_mul_f32 v[30:31], v[30:31], v[0:1] op_sel_hi:[1,0]
	v_pk_mul_f32 v[28:29], v[28:29], v[0:1] op_sel_hi:[1,0]
	v_pk_mul_f32 v[26:27], v[26:27], v[0:1] op_sel_hi:[1,0]
	v_pk_mul_f32 v[24:25], v[24:25], v[0:1] op_sel_hi:[1,0]
	v_pk_mul_f32 v[22:23], v[22:23], v[0:1] op_sel_hi:[1,0]
	v_pk_mul_f32 v[20:21], v[20:21], v[0:1] op_sel_hi:[1,0]
	v_pk_mul_f32 v[18:19], v[18:19], v[0:1] op_sel_hi:[1,0]
	v_pk_mul_f32 v[16:17], v[16:17], v[0:1] op_sel_hi:[1,0]
	v_pk_mul_f32 v[14:15], v[14:15], v[0:1] op_sel_hi:[1,0]
	v_pk_mul_f32 v[12:13], v[12:13], v[0:1] op_sel_hi:[1,0]
	v_pk_mul_f32 v[10:11], v[10:11], v[0:1] op_sel_hi:[1,0]
	v_pk_mul_f32 v[8:9], v[8:9], v[0:1] op_sel_hi:[1,0]
	v_pk_mul_f32 v[6:7], v[6:7], v[0:1] op_sel_hi:[1,0]
	v_pk_mul_f32 v[4:5], v[4:5], v[0:1] op_sel_hi:[1,0]
	v_pk_mul_f32 v[2:3], v[2:3], v[0:1] op_sel_hi:[1,0]
	v_mul_f32_e32 v162, v162, v0
	s_branch .LBB0_1058

.LBB0_1072:
	s_add_i32 s1, s54, 3
	s_cmp_lt_u32 s1, s44
	s_cselect_b32 s1, s1, s45
	s_lshl_b32 s8, s1, 6
	v_add_u32_e32 v2, s8, v174
	v_ashrrev_i32_e32 v3, 31, v2
	v_lshlrev_b64 v[2:3], 10, v[2:3]
	v_lshl_add_u64 v[6:7], s[8:9], 1, v[176:177]
	v_lshl_add_u64 v[2:3], v[182:183], 0, v[2:3]
	v_lshl_add_u64 v[4:5], v[6:7], 0, v[178:179]
	v_lshl_add_u64 v[6:7], v[6:7], 0, v[180:181]
	global_load_dwordx4 v[10:13], v[2:3], off
	s_nop 0
	global_load_dwordx4 v[2:5], v[4:5], off
	s_add_i32 s57, s48, s54
	global_load_dwordx4 v[6:9], v[6:7], off
	s_cmp_lt_i32 s57, 0
	s_cselect_b64 s[16:17], -1, 0
	s_add_i32 s56, s49, s47
	s_cmp_le_i32 s56, s46
	s_cselect_b64 s[4:5], -1, 0
	s_or_b64 s[18:19], s[16:17], s[4:5]
	s_mov_b32 s55, s51
	s_not_b64 s[4:5], s[18:19]
	s_andn2_b64 vcc, exec, s[18:19]
	s_mov_b32 s51, s0
	v_add_u32_e32 v248, s51, v190
	ds_read_b128 v[196:199], v248 offset:9216
	ds_read_b128 v[200:203], v248 offset:13824
	ds_read_b128 v[204:207], v248 offset:18432
	ds_read_b128 v[208:211], v248 offset:23040
	ds_read_b128 v[212:215], v248 offset:9248
	ds_read_b128 v[216:219], v248 offset:13856
	ds_read_b128 v[220:223], v248 offset:18464
	ds_read_b128 v[224:227], v248 offset:23072
	s_cbranch_vccnz .LBB0_1084
	s_cmp_lt_i32 s57, 0
	s_cbranch_scc0 .Ldiff_a_mask
.LBB0_1075:
	v_max3_f32 v0, v80, v81, v82
	v_max3_f32 v14, v96, v97, v98
	v_max3_f32 v0, v0, v83, v84
	v_max3_f32 v14, v14, v99, v100
	v_max3_f32 v0, v0, v85, v86
	v_max3_f32 v14, v14, v101, v102
	v_max3_f32 v0, v0, v87, v88
	v_max3_f32 v14, v14, v103, v104
	v_max3_f32 v0, v0, v89, v90
	v_max3_f32 v14, v14, v105, v106
	v_max3_f32 v0, v0, v91, v92
	v_max3_f32 v14, v14, v107, v108
	v_max_f32_e32 v15, v111, v111
	v_max_f32_e32 v156, v95, v95
	v_max3_f32 v0, v0, v93, v94
	v_max3_f32 v14, v14, v109, v110
	v_max_f32_e32 v15, v156, v15
	v_max3_f32 v0, v0, v14, v15
	s_cmp_lg_u32 s47, 0
	s_cselect_b64 s[18:19], -1, 0
	s_cmp_eq_u32 s47, 0
	s_cbranch_scc1 .Ldiff_a_xchg
	v_cmp_lt_f32_e32 vcc, s33, v0
	s_cbranch_vccnz .Ldiff_a_xchg

.LBB0_1088:
	s_setprio 0
	s_add_i32 s0, s54, 4
	s_cmp_lt_u32 s54, s43
	s_cselect_b32 s0, s0, s45
	s_lshl_b32 s8, s0, 6
	v_add_u32_e32 v14, s8, v174
	v_ashrrev_i32_e32 v15, 31, v14
	v_lshlrev_b64 v[14:15], 10, v[14:15]
	v_lshl_add_u64 v[132:133], s[8:9], 1, v[176:177]
	s_waitcnt lgkmcnt(0)
	s_barrier
	v_lshl_add_u64 v[14:15], v[182:183], 0, v[14:15]
	v_lshl_add_u64 v[128:129], v[132:133], 0, v[178:179]
	global_load_dwordx4 v[136:139], v[14:15], off
	s_nop 0
	global_load_dwordx4 v[128:131], v[128:129], off
	v_lshl_add_u64 v[14:15], v[132:133], 0, v[180:181]
	global_load_dwordx4 v[132:135], v[14:15], off
	v_add_u32_e32 v248, s55, v190
	ds_read_b128 v[196:199], v248 offset:9216
	ds_read_b128 v[200:203], v248 offset:13824
	ds_read_b128 v[204:207], v248 offset:18432
	ds_read_b128 v[208:211], v248 offset:23040
	ds_read_b128 v[212:215], v248 offset:9248
	ds_read_b128 v[216:219], v248 offset:13856
	ds_read_b128 v[220:223], v248 offset:18464
	ds_read_b128 v[224:227], v248 offset:23072
	s_add_i32 s57, s57, 1
	s_cmp_lt_i32 s57, 0
	s_cselect_b64 s[0:1], -1, 0
	s_add_i32 s4, s56, 64
	s_cmp_le_i32 s4, s46
	s_cselect_b64 s[4:5], -1, 0
	s_or_b64 s[0:1], s[0:1], s[4:5]
	s_not_b64 s[4:5], s[0:1]
	s_andn2_b64 vcc, exec, s[0:1]
	s_cbranch_vccnz .LBB0_1094
	s_cmp_lt_i32 s57, 0
	s_cbranch_scc0 .Ldiff_b_mask
.LBB0_1091:
	v_max3_f32 v14, v80, v81, v82
	v_max3_f32 v15, v96, v97, v98
	v_max3_f32 v14, v14, v83, v84
	v_max3_f32 v15, v15, v99, v100
	v_max3_f32 v14, v14, v85, v86
	v_max3_f32 v15, v15, v101, v102
	v_max3_f32 v14, v14, v87, v88
	v_max3_f32 v15, v15, v103, v104
	v_max3_f32 v14, v14, v89, v90
	v_max3_f32 v15, v15, v105, v106
	v_max3_f32 v14, v14, v91, v92
	v_max3_f32 v15, v15, v107, v108
	v_max_f32_e32 v140, v111, v111
	v_max_f32_e32 v141, v95, v95
	v_max3_f32 v14, v14, v93, v94
	v_max3_f32 v15, v15, v109, v110
	v_max_f32_e32 v140, v141, v140
	v_max3_f32 v14, v14, v15, v140
	v_cmp_lt_f32_e32 vcc, s33, v14
	s_cbranch_vccnz .Ldiff_b_resc

.Ldiff_a_mask:
	v_add_u32_e32 v0, s47, v194
	v_add_u32_e32 v14, 32, v0
	v_cmp_le_i32_e32 vcc, v14, v192
	v_add_u32_e32 v14, 33, v0
	s_nop 0
	v_cndmask_b32_e32 v96, v185, v96, vcc
	v_cmp_lt_i32_e32 vcc, v0, v192
	s_nop 1
	v_cndmask_b32_e32 v81, v185, v81, vcc
	v_cmp_le_i32_e32 vcc, v0, v192
	s_nop 1
	v_cndmask_b32_e32 v80, v185, v80, vcc
	v_cmp_le_i32_e32 vcc, v14, v192
	v_add_u32_e32 v14, 2, v0
	s_nop 0
	v_cndmask_b32_e32 v97, v185, v97, vcc
	v_cmp_le_i32_e32 vcc, v14, v192
	v_add_u32_e32 v14, 34, v0
	s_nop 0
	v_cndmask_b32_e32 v82, v185, v82, vcc
	v_cmp_le_i32_e32 vcc, v14, v192
	v_add_u32_e32 v14, 3, v0
	s_nop 0
	v_cndmask_b32_e32 v98, v185, v98, vcc
	v_cmp_le_i32_e32 vcc, v14, v192
	v_add_u32_e32 v14, 35, v0
	s_nop 0
	v_cndmask_b32_e32 v83, v185, v83, vcc
	v_cmp_le_i32_e32 vcc, v14, v192
	v_add_u32_e32 v14, 8, v0
	s_nop 0
	v_cndmask_b32_e32 v99, v185, v99, vcc
	v_cmp_le_i32_e32 vcc, v14, v192
	v_add_u32_e32 v14, 40, v0
	s_nop 0
	v_cndmask_b32_e32 v84, v185, v84, vcc
	v_cmp_le_i32_e32 vcc, v14, v192
	v_add_u32_e32 v14, 9, v0
	s_nop 0
	v_cndmask_b32_e32 v100, v185, v100, vcc
	v_cmp_le_i32_e32 vcc, v14, v192
	v_add_u32_e32 v14, 41, v0
	s_nop 0
	v_cndmask_b32_e32 v85, v185, v85, vcc
	v_cmp_le_i32_e32 vcc, v14, v192
	v_add_u32_e32 v14, 10, v0
	s_nop 0
	v_cndmask_b32_e32 v101, v185, v101, vcc
	v_cmp_le_i32_e32 vcc, v14, v192
	v_add_u32_e32 v14, 42, v0
	s_nop 0
	v_cndmask_b32_e32 v86, v185, v86, vcc
	v_cmp_le_i32_e32 vcc, v14, v192
	v_add_u32_e32 v14, 11, v0
	s_nop 0
	v_cndmask_b32_e32 v102, v185, v102, vcc
	v_cmp_le_i32_e32 vcc, v14, v192
	v_add_u32_e32 v14, 43, v0
	s_nop 0
	v_cndmask_b32_e32 v87, v185, v87, vcc
	v_cmp_le_i32_e32 vcc, v14, v192
	v_add_u32_e32 v14, 16, v0
	s_nop 0
	v_cndmask_b32_e32 v103, v185, v103, vcc
	v_cmp_le_i32_e32 vcc, v14, v192
	v_add_u32_e32 v14, 48, v0
	s_nop 0
	v_cndmask_b32_e32 v88, v185, v88, vcc
	v_cmp_le_i32_e32 vcc, v14, v192
	v_add_u32_e32 v14, 17, v0
	s_nop 0
	v_cndmask_b32_e32 v104, v185, v104, vcc
	v_cmp_le_i32_e32 vcc, v14, v192
	v_add_u32_e32 v14, 49, v0
	s_nop 0
	v_cndmask_b32_e32 v89, v185, v89, vcc
	v_cmp_le_i32_e32 vcc, v14, v192
	v_add_u32_e32 v14, 18, v0
	s_nop 0
	v_cndmask_b32_e32 v105, v185, v105, vcc
	v_cmp_le_i32_e32 vcc, v14, v192
	v_add_u32_e32 v14, 50, v0
	s_nop 0
	v_cndmask_b32_e32 v90, v185, v90, vcc
	v_cmp_le_i32_e32 vcc, v14, v192
	v_add_u32_e32 v14, 19, v0
	s_nop 0
	v_cndmask_b32_e32 v106, v185, v106, vcc
	v_cmp_le_i32_e32 vcc, v14, v192
	v_add_u32_e32 v14, 51, v0
	s_nop 0
	v_cndmask_b32_e32 v91, v185, v91, vcc
	v_cmp_le_i32_e32 vcc, v14, v192
	v_add_u32_e32 v14, 24, v0
	s_nop 0
	v_cndmask_b32_e32 v107, v185, v107, vcc
	v_cmp_le_i32_e32 vcc, v14, v192
	v_add_u32_e32 v14, 56, v0
	s_nop 0
	v_cndmask_b32_e32 v92, v185, v92, vcc
	v_cmp_le_i32_e32 vcc, v14, v192
	v_add_u32_e32 v14, 25, v0
	s_nop 0
	v_cndmask_b32_e32 v108, v185, v108, vcc
	v_cmp_le_i32_e32 vcc, v14, v192
	v_add_u32_e32 v14, 57, v0
	s_nop 0
	v_cndmask_b32_e32 v93, v185, v93, vcc
	v_cmp_le_i32_e32 vcc, v14, v192
	v_add_u32_e32 v14, 26, v0
	s_nop 0
	v_cndmask_b32_e32 v109, v185, v109, vcc
	v_cmp_le_i32_e32 vcc, v14, v192
	v_add_u32_e32 v14, 58, v0
	s_nop 0
	v_cndmask_b32_e32 v94, v185, v94, vcc
	v_cmp_le_i32_e32 vcc, v14, v192
	v_add_u32_e32 v14, 27, v0
	v_add_u32_e32 v0, 59, v0
	v_cndmask_b32_e32 v110, v185, v110, vcc
	v_cmp_le_i32_e32 vcc, v14, v192
	s_nop 1
	v_cndmask_b32_e32 v95, v185, v95, vcc
	v_cmp_le_i32_e32 vcc, v0, v192
	s_nop 1
	v_cndmask_b32_e32 v111, v185, v111, vcc
	s_branch .LBB0_1075

.LBB0_1082:
	v_add_f32_e32 v195, v195, v0
	v_xor_b32_e32 v112, 0x80000000, v195
	v_sub_f32_e32 v95, v95, v0
	v_sub_f32_e32 v94, v94, v0
	v_sub_f32_e32 v93, v93, v0
	v_sub_f32_e32 v92, v92, v0
	v_sub_f32_e32 v91, v91, v0
	v_sub_f32_e32 v90, v90, v0
	v_sub_f32_e32 v89, v89, v0
	v_sub_f32_e32 v88, v88, v0
	v_sub_f32_e32 v87, v87, v0
	v_sub_f32_e32 v86, v86, v0
	v_sub_f32_e32 v85, v85, v0
	v_sub_f32_e32 v84, v84, v0
	v_sub_f32_e32 v83, v83, v0
	v_sub_f32_e32 v82, v82, v0
	v_sub_f32_e32 v81, v81, v0
	v_sub_f32_e32 v80, v80, v0
	v_sub_f32_e32 v111, v111, v0
	v_sub_f32_e32 v110, v110, v0
	v_sub_f32_e32 v109, v109, v0
	v_sub_f32_e32 v108, v108, v0
	v_sub_f32_e32 v107, v107, v0
	v_sub_f32_e32 v106, v106, v0
	v_sub_f32_e32 v105, v105, v0
	v_sub_f32_e32 v104, v104, v0
	v_sub_f32_e32 v103, v103, v0
	v_sub_f32_e32 v102, v102, v0
	v_sub_f32_e32 v101, v101, v0
	v_sub_f32_e32 v100, v100, v0
	v_sub_f32_e32 v99, v99, v0
	v_sub_f32_e32 v98, v98, v0
	v_sub_f32_e32 v97, v97, v0
	v_sub_f32_e32 v96, v96, v0
	v_mov_b32_e32 v113, v112
	v_mov_b32_e32 v114, v112
	v_mov_b32_e32 v115, v112
	v_mov_b32_e32 v116, v112
	v_mov_b32_e32 v117, v112
	v_mov_b32_e32 v118, v112
	v_mov_b32_e32 v119, v112
	v_mov_b32_e32 v120, v112
	v_mov_b32_e32 v121, v112
	v_mov_b32_e32 v122, v112
	v_mov_b32_e32 v123, v112
	v_mov_b32_e32 v124, v112
	v_mov_b32_e32 v125, v112
	v_mov_b32_e32 v126, v112
	v_mov_b32_e32 v127, v112
	s_branch .LBB0_1083
.Ldiff_b_mask:
	v_add_u32_e32 v14, s47, v194
	v_add_u32_e32 v140, 0x60, v14
	v_add_u32_e32 v15, 64, v14
	v_cmp_le_i32_e32 vcc, v140, v192
	s_nop 1
	v_cndmask_b32_e32 v96, v185, v96, vcc
	v_cmp_lt_i32_e32 vcc, v15, v192
	s_nop 1
	v_cndmask_b32_e32 v81, v185, v81, vcc
	v_cmp_le_i32_e32 vcc, v15, v192
	v_add_u32_e32 v15, 0x61, v14
	s_nop 0
	v_cndmask_b32_e32 v80, v185, v80, vcc
	v_cmp_le_i32_e32 vcc, v15, v192
	v_add_u32_e32 v15, 0x42, v14
	s_nop 0
	v_cndmask_b32_e32 v97, v185, v97, vcc
	v_cmp_le_i32_e32 vcc, v15, v192
	v_add_u32_e32 v15, 0x62, v14
	s_nop 0
	v_cndmask_b32_e32 v82, v185, v82, vcc
	v_cmp_le_i32_e32 vcc, v15, v192
	v_add_u32_e32 v15, 0x43, v14
	s_nop 0
	v_cndmask_b32_e32 v98, v185, v98, vcc
	v_cmp_le_i32_e32 vcc, v15, v192
	v_add_u32_e32 v15, 0x63, v14
	s_nop 0
	v_cndmask_b32_e32 v83, v185, v83, vcc
	v_cmp_le_i32_e32 vcc, v15, v192
	v_add_u32_e32 v15, 0x48, v14
	s_nop 0
	v_cndmask_b32_e32 v99, v185, v99, vcc
	v_cmp_le_i32_e32 vcc, v15, v192
	v_add_u32_e32 v15, 0x68, v14
	s_nop 0
	v_cndmask_b32_e32 v84, v185, v84, vcc
	v_cmp_le_i32_e32 vcc, v15, v192
	v_add_u32_e32 v15, 0x49, v14
	s_nop 0
	v_cndmask_b32_e32 v100, v185, v100, vcc
	v_cmp_le_i32_e32 vcc, v15, v192
	v_add_u32_e32 v15, 0x69, v14
	s_nop 0
	v_cndmask_b32_e32 v85, v185, v85, vcc
	v_cmp_le_i32_e32 vcc, v15, v192
	v_add_u32_e32 v15, 0x4a, v14
	s_nop 0
	v_cndmask_b32_e32 v101, v185, v101, vcc
	v_cmp_le_i32_e32 vcc, v15, v192
	v_add_u32_e32 v15, 0x6a, v14
	s_nop 0
	v_cndmask_b32_e32 v86, v185, v86, vcc
	v_cmp_le_i32_e32 vcc, v15, v192
	v_add_u32_e32 v15, 0x4b, v14
	s_nop 0
	v_cndmask_b32_e32 v102, v185, v102, vcc
	v_cmp_le_i32_e32 vcc, v15, v192
	v_add_u32_e32 v15, 0x6b, v14
	s_nop 0
	v_cndmask_b32_e32 v87, v185, v87, vcc
	v_cmp_le_i32_e32 vcc, v15, v192
	v_add_u32_e32 v15, 0x50, v14
	s_nop 0
	v_cndmask_b32_e32 v103, v185, v103, vcc
	v_cmp_le_i32_e32 vcc, v15, v192
	v_add_u32_e32 v15, 0x70, v14
	s_nop 0
	v_cndmask_b32_e32 v88, v185, v88, vcc
	v_cmp_le_i32_e32 vcc, v15, v192
	v_add_u32_e32 v15, 0x51, v14
	s_nop 0
	v_cndmask_b32_e32 v104, v185, v104, vcc
	v_cmp_le_i32_e32 vcc, v15, v192
	v_add_u32_e32 v15, 0x71, v14
	s_nop 0
	v_cndmask_b32_e32 v89, v185, v89, vcc
	v_cmp_le_i32_e32 vcc, v15, v192
	v_add_u32_e32 v15, 0x52, v14
	s_nop 0
	v_cndmask_b32_e32 v105, v185, v105, vcc
	v_cmp_le_i32_e32 vcc, v15, v192
	v_add_u32_e32 v15, 0x72, v14
	s_nop 0
	v_cndmask_b32_e32 v90, v185, v90, vcc
	v_cmp_le_i32_e32 vcc, v15, v192
	v_add_u32_e32 v15, 0x53, v14
	s_nop 0
	v_cndmask_b32_e32 v106, v185, v106, vcc
	v_cmp_le_i32_e32 vcc, v15, v192
	v_add_u32_e32 v15, 0x73, v14
	s_nop 0
	v_cndmask_b32_e32 v91, v185, v91, vcc
	v_cmp_le_i32_e32 vcc, v15, v192
	v_add_u32_e32 v15, 0x58, v14
	s_nop 0
	v_cndmask_b32_e32 v107, v185, v107, vcc
	v_cmp_le_i32_e32 vcc, v15, v192
	v_add_u32_e32 v15, 0x78, v14
	s_nop 0
	v_cndmask_b32_e32 v92, v185, v92, vcc
	v_cmp_le_i32_e32 vcc, v15, v192
	v_add_u32_e32 v15, 0x59, v14
	s_nop 0
	v_cndmask_b32_e32 v108, v185, v108, vcc
	v_cmp_le_i32_e32 vcc, v15, v192
	v_add_u32_e32 v15, 0x79, v14
	s_nop 0
	v_cndmask_b32_e32 v93, v185, v93, vcc
	v_cmp_le_i32_e32 vcc, v15, v192
	v_add_u32_e32 v15, 0x5a, v14
	s_nop 0
	v_cndmask_b32_e32 v109, v185, v109, vcc
	v_cmp_le_i32_e32 vcc, v15, v192
	v_add_u32_e32 v15, 0x7a, v14
	s_nop 0
	v_cndmask_b32_e32 v94, v185, v94, vcc
	v_cmp_le_i32_e32 vcc, v15, v192
	v_add_u32_e32 v15, 0x5b, v14
	v_add_u32_e32 v14, 0x7b, v14
	v_cndmask_b32_e32 v110, v185, v110, vcc
	v_cmp_le_i32_e32 vcc, v15, v192
	s_nop 1
	v_cndmask_b32_e32 v95, v185, v95, vcc
	v_cmp_le_i32_e32 vcc, v14, v192
	s_nop 1
	v_cndmask_b32_e32 v111, v185, v111, vcc
	s_branch .LBB0_1091
.Ldiff_b_resc:
	ds_bpermute_b32 v15, v184, v14
	s_waitcnt lgkmcnt(0)
	v_max_f32_e32 v15, v15, v15
	v_max_f32_e32 v14, v14, v15
	v_max_f32_e32 v14, v14, v14
	v_max_f32_e32 v15, 0, v14
	v_exp_f32_e64 v14, -v15
	v_add_f32_e32 v195, v195, v15
	v_xor_b32_e32 v112, 0x80000000, v195
	v_sub_f32_e32 v95, v95, v15
	v_sub_f32_e32 v94, v94, v15
	v_sub_f32_e32 v93, v93, v15
	v_sub_f32_e32 v92, v92, v15
	v_sub_f32_e32 v91, v91, v15
	v_sub_f32_e32 v90, v90, v15
	v_sub_f32_e32 v89, v89, v15
	v_sub_f32_e32 v88, v88, v15
	v_sub_f32_e32 v87, v87, v15
	v_sub_f32_e32 v86, v86, v15
	v_sub_f32_e32 v85, v85, v15
	v_sub_f32_e32 v84, v84, v15
	v_sub_f32_e32 v83, v83, v15
	v_sub_f32_e32 v82, v82, v15
	v_sub_f32_e32 v81, v81, v15
	v_sub_f32_e32 v80, v80, v15
	v_pk_mul_f32 v[78:79], v[78:79], v[14:15] op_sel_hi:[1,0]
	v_pk_mul_f32 v[76:77], v[76:77], v[14:15] op_sel_hi:[1,0]
	v_pk_mul_f32 v[74:75], v[74:75], v[14:15] op_sel_hi:[1,0]
	v_pk_mul_f32 v[72:73], v[72:73], v[14:15] op_sel_hi:[1,0]
	v_pk_mul_f32 v[70:71], v[70:71], v[14:15] op_sel_hi:[1,0]
	v_pk_mul_f32 v[68:69], v[68:69], v[14:15] op_sel_hi:[1,0]
	v_pk_mul_f32 v[66:67], v[66:67], v[14:15] op_sel_hi:[1,0]
	v_pk_mul_f32 v[64:65], v[64:65], v[14:15] op_sel_hi:[1,0]
	v_pk_mul_f32 v[62:63], v[62:63], v[14:15] op_sel_hi:[1,0]
	v_pk_mul_f32 v[60:61], v[60:61], v[14:15] op_sel_hi:[1,0]
	v_pk_mul_f32 v[58:59], v[58:59], v[14:15] op_sel_hi:[1,0]
	v_pk_mul_f32 v[56:57], v[56:57], v[14:15] op_sel_hi:[1,0]
	v_pk_mul_f32 v[54:55], v[54:55], v[14:15] op_sel_hi:[1,0]
	v_pk_mul_f32 v[52:53], v[52:53], v[14:15] op_sel_hi:[1,0]
	v_pk_mul_f32 v[50:51], v[50:51], v[14:15] op_sel_hi:[1,0]
	v_pk_mul_f32 v[48:49], v[48:49], v[14:15] op_sel_hi:[1,0]
	v_pk_mul_f32 v[46:47], v[46:47], v[14:15] op_sel_hi:[1,0]
	v_pk_mul_f32 v[44:45], v[44:45], v[14:15] op_sel_hi:[1,0]
	v_pk_mul_f32 v[42:43], v[42:43], v[14:15] op_sel_hi:[1,0]
	v_pk_mul_f32 v[40:41], v[40:41], v[14:15] op_sel_hi:[1,0]
	v_pk_mul_f32 v[38:39], v[38:39], v[14:15] op_sel_hi:[1,0]
	v_pk_mul_f32 v[36:37], v[36:37], v[14:15] op_sel_hi:[1,0]
	v_pk_mul_f32 v[34:35], v[34:35], v[14:15] op_sel_hi:[1,0]
	v_pk_mul_f32 v[32:33], v[32:33], v[14:15] op_sel_hi:[1,0]
	v_pk_mul_f32 v[30:31], v[30:31], v[14:15] op_sel_hi:[1,0]
	v_pk_mul_f32 v[28:29], v[28:29], v[14:15] op_sel_hi:[1,0]
	v_pk_mul_f32 v[26:27], v[26:27], v[14:15] op_sel_hi:[1,0]
	v_pk_mul_f32 v[24:25], v[24:25], v[14:15] op_sel_hi:[1,0]
	v_pk_mul_f32 v[22:23], v[22:23], v[14:15] op_sel_hi:[1,0]
	v_pk_mul_f32 v[20:21], v[20:21], v[14:15] op_sel_hi:[1,0]
	v_pk_mul_f32 v[18:19], v[18:19], v[14:15] op_sel_hi:[1,0]
	v_pk_mul_f32 v[16:17], v[16:17], v[14:15] op_sel_hi:[1,0]
	v_sub_f32_e32 v111, v111, v15
	v_sub_f32_e32 v110, v110, v15
	v_sub_f32_e32 v109, v109, v15
	v_sub_f32_e32 v108, v108, v15
	v_sub_f32_e32 v107, v107, v15
	v_sub_f32_e32 v106, v106, v15
	v_sub_f32_e32 v105, v105, v15
	v_sub_f32_e32 v104, v104, v15
	v_sub_f32_e32 v103, v103, v15
	v_sub_f32_e32 v102, v102, v15
	v_sub_f32_e32 v101, v101, v15
	v_sub_f32_e32 v100, v100, v15
	v_sub_f32_e32 v99, v99, v15
	v_sub_f32_e32 v98, v98, v15
	v_sub_f32_e32 v97, v97, v15
	v_sub_f32_e32 v96, v96, v15
	v_mov_b32_e32 v113, v112
	v_mov_b32_e32 v114, v112
	v_mov_b32_e32 v115, v112
	v_mov_b32_e32 v116, v112
	v_mov_b32_e32 v117, v112
	v_mov_b32_e32 v118, v112
	v_mov_b32_e32 v119, v112
	v_mov_b32_e32 v120, v112
	v_mov_b32_e32 v121, v112
	v_mov_b32_e32 v122, v112
	v_mov_b32_e32 v123, v112
	v_mov_b32_e32 v124, v112
	v_mov_b32_e32 v125, v112
	v_mov_b32_e32 v126, v112
	v_mov_b32_e32 v127, v112
	v_mul_f32_e32 v193, v193, v14
	s_branch .LBB0_1093
